# row-norm phases (7, 10, 16, 19): non-temporal (nt) source loads, so the freshly written bf16 rows stay in L2 for the next GEMM
# speedup vs baseline: 1.0113x; 1.0113x over previous
; DI void phase_rmsnorm(const Ctx& c, const float* src, const float* w) {
;     ...
;   for (int u = blockIdx.x; u < NTOK / 8; u += gridDim.x) {
;     const int row = u * 8 + wid * 2;
;     const float* xr = src + (size_t)row * 1024;
;     f32x4 v[2][4];
; #pragma unroll
;     for (int r = 0; r < 2; ++r)
; #pragma unroll
;       for (int i = 0; i < 4; ++i) v[r][i] = *(const f32x4*)(xr + r * 1024 + i * 256 + lane * 4);
; #pragma unroll
;     for (int r = 0; r < 2; ++r) {
;       float ss = 0.f;
; #pragma unroll
;       for (int i = 0; i < 4; ++i) ss += v[r][i][0] * v[r][i][0] + v[r][i][1] * v[r][i][1] + v[r][i][2] * v[r][i][2] + v[r][i][3] * v[r][i][3];
;       ss = wave_sum(ss);
;       const float rs = rsqrtf(ss * (1.0f / 1024.0f) + 1e-5f);
.LBB0_886:
	v_ashrrev_i32_e32 v33, 31, v32
	v_lshlrev_b64 v[16:17], 12, v[32:33]
	v_lshl_add_u64 v[16:17], v[28:29], 0, v[16:17]
	global_load_dwordx4 v[38:41], v[16:17], off nt
	global_load_dwordx4 v[42:45], v[16:17], off offset:1024 nt
	global_load_dwordx4 v[46:49], v[16:17], off offset:2048 nt
	global_load_dwordx4 v[50:53], v[16:17], off offset:3072 nt
	v_add_co_u32_e32 v16, vcc, 0x1000, v16
	s_add_i32 s4, s4, s1
	s_nop 0
	v_addc_co_u32_e32 v17, vcc, 0, v17, vcc
	global_load_dwordx4 v[54:57], v[16:17], off nt
	global_load_dwordx4 v[24:27], v[16:17], off offset:1024 nt
	global_load_dwordx4 v[20:23], v[16:17], off offset:2048 nt
	s_nop 0
	global_load_dwordx4 v[16:19], v[16:17], off offset:3072 nt
	s_cmpk_lt_i32 s4, 0x1000
	s_waitcnt vmcnt(7)
	v_mov_b32_e32 v60, v39
	s_waitcnt vmcnt(6)
	v_mov_b32_e32 v61, v43
	s_waitcnt vmcnt(5)
	v_mov_b32_e32 v68, v47
	s_waitcnt vmcnt(4)
	v_mov_b32_e32 v69, v51
	v_mov_b32_e32 v58, v38
	v_mov_b32_e32 v59, v42
	v_mov_b32_e32 v66, v46
	v_mov_b32_e32 v67, v50
	v_pk_mul_f32 v[60:61], v[60:61], v[60:61]
	v_pk_mul_f32 v[68:69], v[68:69], v[68:69]
	v_mov_b32_e32 v62, v40
	v_mov_b32_e32 v63, v44
	v_pk_fma_f32 v[58:59], v[58:59], v[58:59], v[60:61]
	v_pk_fma_f32 v[60:61], v[66:67], v[66:67], v[68:69]
	s_waitcnt vmcnt(3)
	v_mov_b32_e32 v68, v55
	s_waitcnt vmcnt(2)
	v_mov_b32_e32 v69, v25
	v_mov_b32_e32 v66, v54
	v_mov_b32_e32 v67, v24
	s_waitcnt vmcnt(1)
	v_mov_b32_e32 v80, v21
	s_waitcnt vmcnt(0)
	v_mov_b32_e32 v81, v17
	v_pk_fma_f32 v[58:59], v[62:63], v[62:63], v[58:59]
	v_pk_mul_f32 v[62:63], v[68:69], v[68:69]
	v_mov_b32_e32 v64, v41
	v_mov_b32_e32 v65, v45
	v_mov_b32_e32 v74, v56
	v_mov_b32_e32 v75, v26
	v_mov_b32_e32 v78, v20
	v_mov_b32_e32 v79, v16
	v_pk_mul_f32 v[68:69], v[80:81], v[80:81]
	v_pk_fma_f32 v[62:63], v[66:67], v[66:67], v[62:63]
	v_mov_b32_e32 v70, v48
	v_mov_b32_e32 v71, v52
	v_mov_b32_e32 v76, v57
	v_mov_b32_e32 v77, v27
	v_mov_b32_e32 v82, v22
	v_mov_b32_e32 v83, v18
	v_pk_fma_f32 v[58:59], v[64:65], v[64:65], v[58:59]
	v_pk_fma_f32 v[64:65], v[78:79], v[78:79], v[68:69]
	v_pk_fma_f32 v[62:63], v[74:75], v[74:75], v[62:63]
	v_mov_b32_e32 v72, v49
	v_mov_b32_e32 v73, v53
	v_mov_b32_e32 v84, v23
	v_mov_b32_e32 v85, v19
	v_pk_fma_f32 v[60:61], v[70:71], v[70:71], v[60:61]
	v_pk_fma_f32 v[64:65], v[82:83], v[82:83], v[64:65]
	v_pk_fma_f32 v[62:63], v[76:77], v[76:77], v[62:63]
	v_pk_fma_f32 v[60:61], v[72:73], v[72:73], v[60:61]
	v_mov_b32_e32 v67, v58
	v_pk_fma_f32 v[64:65], v[84:85], v[84:85], v[64:65]
	v_mov_b32_e32 v66, v62
	v_mov_b32_e32 v58, v63
	v_mov_b32_e32 v69, v60
	v_mov_b32_e32 v68, v64
	v_pk_add_f32 v[58:59], v[66:67], v[58:59]
	v_mov_b32_e32 v60, v65
	v_pk_add_f32 v[58:59], v[58:59], v[68:69]
	s_nop 0
	v_pk_add_f32 v[58:59], v[58:59], v[60:61]
	s_nop 1
	v_mov_b32_dpp v61, v59 quad_perm:[1,0,3,2] row_mask:0xf bank_mask:0xf bound_ctrl:1
	v_mov_b32_dpp v60, v58 quad_perm:[1,0,3,2] row_mask:0xf bank_mask:0xf bound_ctrl:1
	v_pk_add_f32 v[58:59], v[58:59], v[60:61]
	s_nop 1
	v_mov_b32_dpp v61, v59 quad_perm:[2,3,0,1] row_mask:0xf bank_mask:0xf bound_ctrl:1
	v_mov_b32_dpp v60, v58 quad_perm:[2,3,0,1] row_mask:0xf bank_mask:0xf bound_ctrl:1
	v_pk_add_f32 v[58:59], v[58:59], v[60:61]
	s_nop 1
	v_mov_b32_dpp v61, v59 row_half_mirror row_mask:0xf bank_mask:0xf bound_ctrl:1
	v_mov_b32_dpp v60, v58 row_half_mirror row_mask:0xf bank_mask:0xf bound_ctrl:1
	v_pk_add_f32 v[58:59], v[58:59], v[60:61]
	s_nop 1
	v_mov_b32_dpp v61, v59 row_mirror row_mask:0xf bank_mask:0xf bound_ctrl:1
	v_mov_b32_dpp v60, v58 row_mirror row_mask:0xf bank_mask:0xf bound_ctrl:1
	v_pk_add_f32 v[58:59], v[58:59], v[60:61]
	ds_bpermute_b32 v61, v36, v59
	ds_bpermute_b32 v60, v36, v58
	s_waitcnt lgkmcnt(0)
; DI unsigned pack2(float lo, float hi) { const f32x2c v = {lo, hi}; return __builtin_bit_cast(unsigned, __builtin_convertvector(v, bf16x2c)); }
; DI void phase_rmsnorm(const Ctx& c, const float* src, const float* w) {
;     ...
;       ss = wave_sum(ss);
;       const float rs = rsqrtf(ss * (1.0f / 1024.0f) + 1e-5f);
;       bf16_t* o = xn + (size_t)(row + r) * 1024;
; #pragma unroll
;       for (int i = 0; i < 4; ++i) { u32x2 q; q.x = pack2(v[r][i][0] * rs * g[i][0], v[r][i][1] * rs * g[i][1]); q.y = pack2(v[r][i][2] * rs * g[i][2], v[r][i][3] * rs * g[i][3]); *(u32x2*)(o + i * 256 + lane * 4) = q; }
;     }
	v_pk_add_f32 v[58:59], v[58:59], v[60:61]
	ds_bpermute_b32 v61, v37, v59
	ds_bpermute_b32 v60, v37, v58
	s_waitcnt lgkmcnt(0)
	v_pk_add_f32 v[58:59], v[58:59], v[60:61]
	s_nop 0
	v_pk_fma_f32 v[58:59], v[58:59], s[0:1], v[34:35] op_sel_hi:[1,0,0]
	s_nop 0
	v_mul_f32_e32 v60, 0x4b800000, v59
	v_cmp_gt_f32_e32 vcc, s3, v59
	s_nop 1
	v_cndmask_b32_e32 v59, v59, v60, vcc
	v_rsq_f32_e32 v59, v59
	v_lshlrev_b64 v[60:61], 11, v[32:33]
	v_mul_f32_e32 v33, 0x4b800000, v58
	v_lshl_add_u64 v[60:61], v[30:31], 0, v[60:61]
	v_mul_f32_e32 v62, 0x45800000, v59
	v_cndmask_b32_e32 v62, v59, v62, vcc
	v_cmp_gt_f32_e32 vcc, s3, v58
	v_pk_mul_f32 v[38:39], v[38:39], v[62:63] op_sel_hi:[1,0]
	v_pk_mul_f32 v[40:41], v[40:41], v[62:63] op_sel_hi:[1,0]
	v_cndmask_b32_e32 v33, v58, v33, vcc
	v_rsq_f32_e32 v33, v33
	v_pk_mul_f32 v[42:43], v[42:43], v[62:63] op_sel_hi:[1,0]
	v_pk_mul_f32 v[44:45], v[44:45], v[62:63] op_sel_hi:[1,0]
	v_pk_mul_f32 v[46:47], v[46:47], v[62:63] op_sel_hi:[1,0]
	v_pk_mul_f32 v[48:49], v[48:49], v[62:63] op_sel_hi:[1,0]
	v_pk_mul_f32 v[38:39], v[12:13], v[38:39]
	v_pk_mul_f32 v[40:41], v[14:15], v[40:41]
	v_pk_mul_f32 v[52:53], v[52:53], v[62:63] op_sel_hi:[1,0]
	v_pk_mul_f32 v[42:43], v[8:9], v[42:43]
	v_pk_mul_f32 v[44:45], v[10:11], v[44:45]
	v_pk_mul_f32 v[46:47], v[4:5], v[46:47]
	v_pk_mul_f32 v[48:49], v[6:7], v[48:49]
	v_cvt_pk_bf16_f32 v38, v38, v39
	v_cvt_pk_bf16_f32 v39, v40, v41
	v_pk_mul_f32 v[50:51], v[50:51], v[62:63] op_sel_hi:[1,0]
	v_cvt_pk_bf16_f32 v40, v42, v43
	v_cvt_pk_bf16_f32 v41, v44, v45
	v_cvt_pk_bf16_f32 v42, v46, v47
	v_cvt_pk_bf16_f32 v43, v48, v49
	global_store_dwordx2 v[60:61], v[38:39], off
	global_store_dwordx2 v[60:61], v[40:41], off offset:512
	global_store_dwordx2 v[60:61], v[42:43], off offset:1024
	v_pk_mul_f32 v[38:39], v[2:3], v[52:53]
	v_pk_mul_f32 v[50:51], v[0:1], v[50:51]
	v_cvt_pk_bf16_f32 v45, v38, v39
	v_mul_f32_e32 v38, 0x45800000, v33
	v_cvt_pk_bf16_f32 v44, v50, v51
	v_cndmask_b32_e32 v38, v33, v38, vcc
	v_add_u32_e32 v40, 1, v32
	global_store_dwordx2 v[60:61], v[44:45], off offset:1536
	v_ashrrev_i32_e32 v41, 31, v40
	v_pk_mul_f32 v[42:43], v[54:55], v[38:39] op_sel_hi:[1,0]
	v_pk_mul_f32 v[44:45], v[56:57], v[38:39] op_sel_hi:[1,0]
	v_pk_mul_f32 v[24:25], v[24:25], v[38:39] op_sel_hi:[1,0]
	v_pk_mul_f32 v[26:27], v[26:27], v[38:39] op_sel_hi:[1,0]
	v_pk_mul_f32 v[20:21], v[20:21], v[38:39] op_sel_hi:[1,0]
	v_pk_mul_f32 v[22:23], v[22:23], v[38:39] op_sel_hi:[1,0]
	v_pk_mul_f32 v[16:17], v[16:17], v[38:39] op_sel_hi:[1,0]
	v_pk_mul_f32 v[18:19], v[18:19], v[38:39] op_sel_hi:[1,0]
	v_lshlrev_b64 v[40:41], 11, v[40:41]
	v_pk_mul_f32 v[42:43], v[12:13], v[42:43]
	v_pk_mul_f32 v[44:45], v[14:15], v[44:45]
	v_pk_mul_f32 v[24:25], v[8:9], v[24:25]
	v_pk_mul_f32 v[26:27], v[10:11], v[26:27]
	v_pk_mul_f32 v[20:21], v[4:5], v[20:21]
	v_pk_mul_f32 v[22:23], v[6:7], v[22:23]
	v_pk_mul_f32 v[16:17], v[0:1], v[16:17]
	v_pk_mul_f32 v[18:19], v[2:3], v[18:19]
	v_lshl_add_u64 v[40:41], v[30:31], 0, v[40:41]
	v_cvt_pk_bf16_f32 v42, v42, v43
	v_cvt_pk_bf16_f32 v43, v44, v45
	v_cvt_pk_bf16_f32 v24, v24, v25
	v_cvt_pk_bf16_f32 v25, v26, v27
	v_cvt_pk_bf16_f32 v20, v20, v21
	v_cvt_pk_bf16_f32 v21, v22, v23
	v_cvt_pk_bf16_f32 v16, v16, v17
	v_cvt_pk_bf16_f32 v17, v18, v19
	v_add_u32_e32 v32, s2, v32
	global_store_dwordx2 v[40:41], v[42:43], off
	global_store_dwordx2 v[40:41], v[24:25], off offset:512
	global_store_dwordx2 v[40:41], v[20:21], off offset:1024
	global_store_dwordx2 v[40:41], v[16:17], off offset:1536
	s_cbranch_scc1 .LBB0_886

; DI void phase_rmsnorm(const Ctx& c, const float* src, const float* w) {
;     ...
;   for (int u = blockIdx.x; u < NTOK / 8; u += gridDim.x) {
;     const int row = u * 8 + wid * 2;
;     const float* xr = src + (size_t)row * 1024;
;     f32x4 v[2][4];
; #pragma unroll
;     for (int r = 0; r < 2; ++r)
; #pragma unroll
;       for (int i = 0; i < 4; ++i) v[r][i] = *(const f32x4*)(xr + r * 1024 + i * 256 + lane * 4);
; #pragma unroll
;     for (int r = 0; r < 2; ++r) {
;       float ss = 0.f;
; #pragma unroll
;       for (int i = 0; i < 4; ++i) ss += v[r][i][0] * v[r][i][0] + v[r][i][1] * v[r][i][1] + v[r][i][2] * v[r][i][2] + v[r][i][3] * v[r][i][3];
;       ss = wave_sum(ss);
;       const float rs = rsqrtf(ss * (1.0f / 1024.0f) + 1e-5f);
.LBB0_960:
	v_ashrrev_i32_e32 v33, 31, v32
	v_lshlrev_b64 v[16:17], 12, v[32:33]
	v_lshl_add_u64 v[16:17], v[28:29], 0, v[16:17]
	global_load_dwordx4 v[38:41], v[16:17], off nt
	global_load_dwordx4 v[42:45], v[16:17], off offset:1024 nt
	global_load_dwordx4 v[46:49], v[16:17], off offset:2048 nt
	global_load_dwordx4 v[50:53], v[16:17], off offset:3072 nt
	v_add_co_u32_e32 v16, vcc, 0x1000, v16
	s_add_i32 s4, s4, s1
	s_nop 0
	v_addc_co_u32_e32 v17, vcc, 0, v17, vcc
	global_load_dwordx4 v[54:57], v[16:17], off nt
	global_load_dwordx4 v[24:27], v[16:17], off offset:1024 nt
	global_load_dwordx4 v[20:23], v[16:17], off offset:2048 nt
	s_nop 0
	global_load_dwordx4 v[16:19], v[16:17], off offset:3072 nt
	s_cmpk_lt_i32 s4, 0x1000
	s_waitcnt vmcnt(7)
	v_mov_b32_e32 v60, v39
	s_waitcnt vmcnt(6)
	v_mov_b32_e32 v61, v43
	s_waitcnt vmcnt(5)
	v_mov_b32_e32 v68, v47
	s_waitcnt vmcnt(4)
	v_mov_b32_e32 v69, v51
	v_mov_b32_e32 v58, v38
	v_mov_b32_e32 v59, v42
	v_mov_b32_e32 v66, v46
	v_mov_b32_e32 v67, v50
	v_pk_mul_f32 v[60:61], v[60:61], v[60:61]
	v_pk_mul_f32 v[68:69], v[68:69], v[68:69]
	v_mov_b32_e32 v62, v40
	v_mov_b32_e32 v63, v44
	v_pk_fma_f32 v[58:59], v[58:59], v[58:59], v[60:61]
	v_pk_fma_f32 v[60:61], v[66:67], v[66:67], v[68:69]
	s_waitcnt vmcnt(3)
	v_mov_b32_e32 v68, v55
	s_waitcnt vmcnt(2)
	v_mov_b32_e32 v69, v25
	v_mov_b32_e32 v66, v54
	v_mov_b32_e32 v67, v24
	s_waitcnt vmcnt(1)
	v_mov_b32_e32 v80, v21
	s_waitcnt vmcnt(0)
	v_mov_b32_e32 v81, v17
	v_pk_fma_f32 v[58:59], v[62:63], v[62:63], v[58:59]
	v_pk_mul_f32 v[62:63], v[68:69], v[68:69]
	v_mov_b32_e32 v64, v41
	v_mov_b32_e32 v65, v45
	v_mov_b32_e32 v74, v56
	v_mov_b32_e32 v75, v26
	v_mov_b32_e32 v78, v20
	v_mov_b32_e32 v79, v16
	v_pk_mul_f32 v[68:69], v[80:81], v[80:81]
	v_pk_fma_f32 v[62:63], v[66:67], v[66:67], v[62:63]
	v_mov_b32_e32 v70, v48
	v_mov_b32_e32 v71, v52
	v_mov_b32_e32 v76, v57
	v_mov_b32_e32 v77, v27
	v_mov_b32_e32 v82, v22
	v_mov_b32_e32 v83, v18
	v_pk_fma_f32 v[58:59], v[64:65], v[64:65], v[58:59]
	v_pk_fma_f32 v[64:65], v[78:79], v[78:79], v[68:69]
	v_pk_fma_f32 v[62:63], v[74:75], v[74:75], v[62:63]
	v_mov_b32_e32 v72, v49
	v_mov_b32_e32 v73, v53
	v_mov_b32_e32 v84, v23
	v_mov_b32_e32 v85, v19
	v_pk_fma_f32 v[60:61], v[70:71], v[70:71], v[60:61]
	v_pk_fma_f32 v[64:65], v[82:83], v[82:83], v[64:65]
	v_pk_fma_f32 v[62:63], v[76:77], v[76:77], v[62:63]
	v_pk_fma_f32 v[60:61], v[72:73], v[72:73], v[60:61]
	v_mov_b32_e32 v67, v58
	v_pk_fma_f32 v[64:65], v[84:85], v[84:85], v[64:65]
	v_mov_b32_e32 v66, v62
	v_mov_b32_e32 v58, v63
	v_mov_b32_e32 v69, v60
	v_mov_b32_e32 v68, v64
	v_pk_add_f32 v[58:59], v[66:67], v[58:59]
	v_mov_b32_e32 v60, v65
	v_pk_add_f32 v[58:59], v[58:59], v[68:69]
	s_nop 0
	v_pk_add_f32 v[58:59], v[58:59], v[60:61]
	s_nop 1
	v_mov_b32_dpp v61, v59 quad_perm:[1,0,3,2] row_mask:0xf bank_mask:0xf bound_ctrl:1
	v_mov_b32_dpp v60, v58 quad_perm:[1,0,3,2] row_mask:0xf bank_mask:0xf bound_ctrl:1
	v_pk_add_f32 v[58:59], v[58:59], v[60:61]
	s_nop 1
	v_mov_b32_dpp v61, v59 quad_perm:[2,3,0,1] row_mask:0xf bank_mask:0xf bound_ctrl:1
	v_mov_b32_dpp v60, v58 quad_perm:[2,3,0,1] row_mask:0xf bank_mask:0xf bound_ctrl:1
	v_pk_add_f32 v[58:59], v[58:59], v[60:61]
	s_nop 1
	v_mov_b32_dpp v61, v59 row_half_mirror row_mask:0xf bank_mask:0xf bound_ctrl:1
	v_mov_b32_dpp v60, v58 row_half_mirror row_mask:0xf bank_mask:0xf bound_ctrl:1
	v_pk_add_f32 v[58:59], v[58:59], v[60:61]
	s_nop 1
	v_mov_b32_dpp v61, v59 row_mirror row_mask:0xf bank_mask:0xf bound_ctrl:1
	v_mov_b32_dpp v60, v58 row_mirror row_mask:0xf bank_mask:0xf bound_ctrl:1
	v_pk_add_f32 v[58:59], v[58:59], v[60:61]
	ds_bpermute_b32 v61, v36, v59
	ds_bpermute_b32 v60, v36, v58
	s_waitcnt lgkmcnt(0)
; DI unsigned pack2(float lo, float hi) { const f32x2c v = {lo, hi}; return __builtin_bit_cast(unsigned, __builtin_convertvector(v, bf16x2c)); }
; DI void phase_rmsnorm(const Ctx& c, const float* src, const float* w) {
;     ...
;       ss = wave_sum(ss);
;       const float rs = rsqrtf(ss * (1.0f / 1024.0f) + 1e-5f);
;       bf16_t* o = xn + (size_t)(row + r) * 1024;
; #pragma unroll
;       for (int i = 0; i < 4; ++i) { u32x2 q; q.x = pack2(v[r][i][0] * rs * g[i][0], v[r][i][1] * rs * g[i][1]); q.y = pack2(v[r][i][2] * rs * g[i][2], v[r][i][3] * rs * g[i][3]); *(u32x2*)(o + i * 256 + lane * 4) = q; }
;     }
	v_pk_add_f32 v[58:59], v[58:59], v[60:61]
	ds_bpermute_b32 v61, v37, v59
	ds_bpermute_b32 v60, v37, v58
	s_waitcnt lgkmcnt(0)
	v_pk_add_f32 v[58:59], v[58:59], v[60:61]
	s_nop 0
	v_pk_fma_f32 v[58:59], v[58:59], s[0:1], v[34:35] op_sel_hi:[1,0,0]
	s_nop 0
	v_mul_f32_e32 v60, 0x4b800000, v59
	v_cmp_gt_f32_e32 vcc, s3, v59
	s_nop 1
	v_cndmask_b32_e32 v59, v59, v60, vcc
	v_rsq_f32_e32 v59, v59
	v_lshlrev_b64 v[60:61], 11, v[32:33]
	v_mul_f32_e32 v33, 0x4b800000, v58
	v_lshl_add_u64 v[60:61], v[30:31], 0, v[60:61]
	v_mul_f32_e32 v62, 0x45800000, v59
	v_cndmask_b32_e32 v62, v59, v62, vcc
	v_cmp_gt_f32_e32 vcc, s3, v58
	v_pk_mul_f32 v[38:39], v[38:39], v[62:63] op_sel_hi:[1,0]
	v_pk_mul_f32 v[40:41], v[40:41], v[62:63] op_sel_hi:[1,0]
	v_cndmask_b32_e32 v33, v58, v33, vcc
	v_rsq_f32_e32 v33, v33
	v_pk_mul_f32 v[42:43], v[42:43], v[62:63] op_sel_hi:[1,0]
	v_pk_mul_f32 v[44:45], v[44:45], v[62:63] op_sel_hi:[1,0]
	v_pk_mul_f32 v[46:47], v[46:47], v[62:63] op_sel_hi:[1,0]
	v_pk_mul_f32 v[48:49], v[48:49], v[62:63] op_sel_hi:[1,0]
	v_pk_mul_f32 v[38:39], v[12:13], v[38:39]
	v_pk_mul_f32 v[40:41], v[14:15], v[40:41]
	v_pk_mul_f32 v[52:53], v[52:53], v[62:63] op_sel_hi:[1,0]
	v_pk_mul_f32 v[42:43], v[4:5], v[42:43]
	v_pk_mul_f32 v[44:45], v[6:7], v[44:45]
	v_pk_mul_f32 v[46:47], v[0:1], v[46:47]
	v_pk_mul_f32 v[48:49], v[2:3], v[48:49]
	v_cvt_pk_bf16_f32 v38, v38, v39
	v_cvt_pk_bf16_f32 v39, v40, v41
	v_pk_mul_f32 v[50:51], v[50:51], v[62:63] op_sel_hi:[1,0]
	v_cvt_pk_bf16_f32 v40, v42, v43
	v_cvt_pk_bf16_f32 v41, v44, v45
	v_cvt_pk_bf16_f32 v42, v46, v47
	v_cvt_pk_bf16_f32 v43, v48, v49
	global_store_dwordx2 v[60:61], v[38:39], off
	global_store_dwordx2 v[60:61], v[40:41], off offset:512
	global_store_dwordx2 v[60:61], v[42:43], off offset:1024
	v_pk_mul_f32 v[38:39], v[10:11], v[52:53]
	v_pk_mul_f32 v[50:51], v[8:9], v[50:51]
	v_cvt_pk_bf16_f32 v45, v38, v39
	v_mul_f32_e32 v38, 0x45800000, v33
	v_cvt_pk_bf16_f32 v44, v50, v51
	v_cndmask_b32_e32 v38, v33, v38, vcc
	v_add_u32_e32 v40, 1, v32
	global_store_dwordx2 v[60:61], v[44:45], off offset:1536
	v_ashrrev_i32_e32 v41, 31, v40
	v_pk_mul_f32 v[42:43], v[54:55], v[38:39] op_sel_hi:[1,0]
	v_pk_mul_f32 v[44:45], v[56:57], v[38:39] op_sel_hi:[1,0]
	v_pk_mul_f32 v[24:25], v[24:25], v[38:39] op_sel_hi:[1,0]
	v_pk_mul_f32 v[26:27], v[26:27], v[38:39] op_sel_hi:[1,0]
	v_pk_mul_f32 v[20:21], v[20:21], v[38:39] op_sel_hi:[1,0]
	v_pk_mul_f32 v[22:23], v[22:23], v[38:39] op_sel_hi:[1,0]
	v_pk_mul_f32 v[16:17], v[16:17], v[38:39] op_sel_hi:[1,0]
	v_pk_mul_f32 v[18:19], v[18:19], v[38:39] op_sel_hi:[1,0]
	v_lshlrev_b64 v[40:41], 11, v[40:41]
	v_pk_mul_f32 v[42:43], v[12:13], v[42:43]
	v_pk_mul_f32 v[44:45], v[14:15], v[44:45]
	v_pk_mul_f32 v[24:25], v[4:5], v[24:25]
	v_pk_mul_f32 v[26:27], v[6:7], v[26:27]
	v_pk_mul_f32 v[20:21], v[0:1], v[20:21]
	v_pk_mul_f32 v[22:23], v[2:3], v[22:23]
	v_pk_mul_f32 v[16:17], v[8:9], v[16:17]
	v_pk_mul_f32 v[18:19], v[10:11], v[18:19]
	v_lshl_add_u64 v[40:41], v[30:31], 0, v[40:41]
	v_cvt_pk_bf16_f32 v42, v42, v43
	v_cvt_pk_bf16_f32 v43, v44, v45
	v_cvt_pk_bf16_f32 v24, v24, v25
	v_cvt_pk_bf16_f32 v25, v26, v27
	v_cvt_pk_bf16_f32 v20, v20, v21
	v_cvt_pk_bf16_f32 v21, v22, v23
	v_cvt_pk_bf16_f32 v16, v16, v17
	v_cvt_pk_bf16_f32 v17, v18, v19
	v_add_u32_e32 v32, s2, v32
	global_store_dwordx2 v[40:41], v[42:43], off
	global_store_dwordx2 v[40:41], v[24:25], off offset:512
	global_store_dwordx2 v[40:41], v[20:21], off offset:1024
	global_store_dwordx2 v[40:41], v[16:17], off offset:1536
	s_cbranch_scc1 .LBB0_960

; DI void phase_rmsnorm(const Ctx& c, const float* src, const float* w) {
;     ...
;   for (int u = blockIdx.x; u < NTOK / 8; u += gridDim.x) {
;     const int row = u * 8 + wid * 2;
;     const float* xr = src + (size_t)row * 1024;
;     f32x4 v[2][4];
; #pragma unroll
;     for (int r = 0; r < 2; ++r)
; #pragma unroll
;       for (int i = 0; i < 4; ++i) v[r][i] = *(const f32x4*)(xr + r * 1024 + i * 256 + lane * 4);
; #pragma unroll
;     for (int r = 0; r < 2; ++r) {
;       float ss = 0.f;
; #pragma unroll
;       for (int i = 0; i < 4; ++i) ss += v[r][i][0] * v[r][i][0] + v[r][i][1] * v[r][i][1] + v[r][i][2] * v[r][i][2] + v[r][i][3] * v[r][i][3];
;       ss = wave_sum(ss);
;       const float rs = rsqrtf(ss * (1.0f / 1024.0f) + 1e-5f);
.LBB0_1875:
	v_ashrrev_i32_e32 v33, 31, v32
	v_lshlrev_b64 v[16:17], 12, v[32:33]
	v_lshl_add_u64 v[16:17], v[28:29], 0, v[16:17]
	global_load_dwordx4 v[38:41], v[16:17], off nt
	global_load_dwordx4 v[42:45], v[16:17], off offset:1024 nt
	global_load_dwordx4 v[46:49], v[16:17], off offset:2048 nt
	global_load_dwordx4 v[50:53], v[16:17], off offset:3072 nt
	v_add_co_u32_e32 v58, vcc, 0x1000, v16
	s_add_i32 s4, s4, s1
	s_nop 0
	v_addc_co_u32_e32 v59, vcc, 0, v17, vcc
	global_load_dwordx4 v[54:57], v[58:59], off nt
	global_load_dwordx4 v[24:27], v[58:59], off offset:1024 nt
	global_load_dwordx4 v[20:23], v[58:59], off offset:2048 nt
	global_load_dwordx4 v[16:19], v[58:59], off offset:3072 nt
	s_cmpk_lt_i32 s4, 0x1000
	s_waitcnt vmcnt(7)
	v_mov_b32_e32 v60, v39
	s_waitcnt vmcnt(6)
	v_mov_b32_e32 v61, v43
	s_waitcnt vmcnt(5)
	v_mov_b32_e32 v68, v47
	s_waitcnt vmcnt(4)
	v_mov_b32_e32 v69, v51
	v_mov_b32_e32 v58, v38
	v_mov_b32_e32 v59, v42
	v_mov_b32_e32 v66, v46
	v_mov_b32_e32 v67, v50
	v_pk_mul_f32 v[60:61], v[60:61], v[60:61]
	v_pk_mul_f32 v[68:69], v[68:69], v[68:69]
	v_mov_b32_e32 v62, v40
	v_mov_b32_e32 v63, v44
	v_pk_fma_f32 v[58:59], v[58:59], v[58:59], v[60:61]
	v_pk_fma_f32 v[60:61], v[66:67], v[66:67], v[68:69]
	s_waitcnt vmcnt(3)
	v_mov_b32_e32 v68, v55
	s_waitcnt vmcnt(2)
	v_mov_b32_e32 v69, v25
	v_mov_b32_e32 v66, v54
	v_mov_b32_e32 v67, v24
	s_waitcnt vmcnt(1)
	v_mov_b32_e32 v80, v21
	s_waitcnt vmcnt(0)
	v_mov_b32_e32 v81, v17
	v_pk_fma_f32 v[58:59], v[62:63], v[62:63], v[58:59]
	v_pk_mul_f32 v[62:63], v[68:69], v[68:69]
	v_mov_b32_e32 v64, v41
	v_mov_b32_e32 v65, v45
	v_mov_b32_e32 v74, v56
	v_mov_b32_e32 v75, v26
	v_mov_b32_e32 v78, v20
	v_mov_b32_e32 v79, v16
	v_pk_mul_f32 v[68:69], v[80:81], v[80:81]
	v_pk_fma_f32 v[62:63], v[66:67], v[66:67], v[62:63]
	v_mov_b32_e32 v70, v48
	v_mov_b32_e32 v71, v52
	v_mov_b32_e32 v76, v57
	v_mov_b32_e32 v77, v27
	v_mov_b32_e32 v82, v22
	v_mov_b32_e32 v83, v18
	v_pk_fma_f32 v[58:59], v[64:65], v[64:65], v[58:59]
	v_pk_fma_f32 v[64:65], v[78:79], v[78:79], v[68:69]
	v_pk_fma_f32 v[62:63], v[74:75], v[74:75], v[62:63]
	v_mov_b32_e32 v72, v49
	v_mov_b32_e32 v73, v53
	v_mov_b32_e32 v84, v23
	v_mov_b32_e32 v85, v19
	v_pk_fma_f32 v[60:61], v[70:71], v[70:71], v[60:61]
	v_pk_fma_f32 v[64:65], v[82:83], v[82:83], v[64:65]
	v_pk_fma_f32 v[62:63], v[76:77], v[76:77], v[62:63]
	v_pk_fma_f32 v[60:61], v[72:73], v[72:73], v[60:61]
	v_mov_b32_e32 v67, v58
	v_pk_fma_f32 v[64:65], v[84:85], v[84:85], v[64:65]
	v_mov_b32_e32 v66, v62
	v_mov_b32_e32 v58, v63
	v_mov_b32_e32 v69, v60
	v_mov_b32_e32 v68, v64
	v_pk_add_f32 v[58:59], v[66:67], v[58:59]
	v_mov_b32_e32 v60, v65
	v_pk_add_f32 v[58:59], v[58:59], v[68:69]
	s_nop 0
	v_pk_add_f32 v[58:59], v[58:59], v[60:61]
	s_nop 1
	v_mov_b32_dpp v61, v59 quad_perm:[1,0,3,2] row_mask:0xf bank_mask:0xf bound_ctrl:1
	v_mov_b32_dpp v60, v58 quad_perm:[1,0,3,2] row_mask:0xf bank_mask:0xf bound_ctrl:1
	v_pk_add_f32 v[58:59], v[58:59], v[60:61]
	s_nop 1
	v_mov_b32_dpp v61, v59 quad_perm:[2,3,0,1] row_mask:0xf bank_mask:0xf bound_ctrl:1
	v_mov_b32_dpp v60, v58 quad_perm:[2,3,0,1] row_mask:0xf bank_mask:0xf bound_ctrl:1
	v_pk_add_f32 v[58:59], v[58:59], v[60:61]
	s_nop 1
	v_mov_b32_dpp v61, v59 row_half_mirror row_mask:0xf bank_mask:0xf bound_ctrl:1
	v_mov_b32_dpp v60, v58 row_half_mirror row_mask:0xf bank_mask:0xf bound_ctrl:1
	v_pk_add_f32 v[58:59], v[58:59], v[60:61]
	s_nop 1
	v_mov_b32_dpp v61, v59 row_mirror row_mask:0xf bank_mask:0xf bound_ctrl:1
	v_mov_b32_dpp v60, v58 row_mirror row_mask:0xf bank_mask:0xf bound_ctrl:1
	v_pk_add_f32 v[58:59], v[58:59], v[60:61]
	ds_bpermute_b32 v61, v36, v59
	ds_bpermute_b32 v60, v36, v58
	s_waitcnt lgkmcnt(0)
; DI unsigned pack2(float lo, float hi) { const f32x2c v = {lo, hi}; return __builtin_bit_cast(unsigned, __builtin_convertvector(v, bf16x2c)); }
; DI void phase_rmsnorm(const Ctx& c, const float* src, const float* w) {
;     ...
;       ss = wave_sum(ss);
;       const float rs = rsqrtf(ss * (1.0f / 1024.0f) + 1e-5f);
;       bf16_t* o = xn + (size_t)(row + r) * 1024;
; #pragma unroll
;       for (int i = 0; i < 4; ++i) { u32x2 q; q.x = pack2(v[r][i][0] * rs * g[i][0], v[r][i][1] * rs * g[i][1]); q.y = pack2(v[r][i][2] * rs * g[i][2], v[r][i][3] * rs * g[i][3]); *(u32x2*)(o + i * 256 + lane * 4) = q; }
;     }
	v_pk_add_f32 v[58:59], v[58:59], v[60:61]
	ds_bpermute_b32 v61, v37, v59
	ds_bpermute_b32 v60, v37, v58
	s_waitcnt lgkmcnt(0)
	v_pk_add_f32 v[58:59], v[58:59], v[60:61]
	s_nop 0
	v_pk_fma_f32 v[58:59], v[58:59], s[0:1], v[34:35] op_sel_hi:[1,0,0]
	s_nop 0
	v_mul_f32_e32 v60, 0x4b800000, v59
	v_cmp_gt_f32_e32 vcc, s3, v59
	s_nop 1
	v_cndmask_b32_e32 v59, v59, v60, vcc
	v_rsq_f32_e32 v59, v59
	v_lshlrev_b64 v[60:61], 11, v[32:33]
	v_mul_f32_e32 v33, 0x4b800000, v58
	v_lshl_add_u64 v[60:61], v[30:31], 0, v[60:61]
	v_mul_f32_e32 v62, 0x45800000, v59
	v_cndmask_b32_e32 v62, v59, v62, vcc
	v_cmp_gt_f32_e32 vcc, s3, v58
	v_pk_mul_f32 v[38:39], v[38:39], v[62:63] op_sel_hi:[1,0]
	v_pk_mul_f32 v[40:41], v[40:41], v[62:63] op_sel_hi:[1,0]
	v_cndmask_b32_e32 v33, v58, v33, vcc
	v_rsq_f32_e32 v33, v33
	v_pk_mul_f32 v[42:43], v[42:43], v[62:63] op_sel_hi:[1,0]
	v_pk_mul_f32 v[44:45], v[44:45], v[62:63] op_sel_hi:[1,0]
	v_pk_mul_f32 v[46:47], v[46:47], v[62:63] op_sel_hi:[1,0]
	v_pk_mul_f32 v[48:49], v[48:49], v[62:63] op_sel_hi:[1,0]
	v_pk_mul_f32 v[38:39], v[12:13], v[38:39]
	v_pk_mul_f32 v[40:41], v[14:15], v[40:41]
	v_pk_mul_f32 v[52:53], v[52:53], v[62:63] op_sel_hi:[1,0]
	v_pk_mul_f32 v[42:43], v[4:5], v[42:43]
	v_pk_mul_f32 v[44:45], v[6:7], v[44:45]
	v_pk_mul_f32 v[46:47], v[0:1], v[46:47]
	v_pk_mul_f32 v[48:49], v[2:3], v[48:49]
	v_cvt_pk_bf16_f32 v38, v38, v39
	v_cvt_pk_bf16_f32 v39, v40, v41
	v_pk_mul_f32 v[50:51], v[50:51], v[62:63] op_sel_hi:[1,0]
	v_cvt_pk_bf16_f32 v40, v42, v43
	v_cvt_pk_bf16_f32 v41, v44, v45
	v_cvt_pk_bf16_f32 v42, v46, v47
	v_cvt_pk_bf16_f32 v43, v48, v49
	global_store_dwordx2 v[60:61], v[38:39], off
	global_store_dwordx2 v[60:61], v[40:41], off offset:512
	global_store_dwordx2 v[60:61], v[42:43], off offset:1024
	v_pk_mul_f32 v[38:39], v[10:11], v[52:53]
	v_pk_mul_f32 v[50:51], v[8:9], v[50:51]
	v_cvt_pk_bf16_f32 v45, v38, v39
	v_mul_f32_e32 v38, 0x45800000, v33
	v_cvt_pk_bf16_f32 v44, v50, v51
	v_cndmask_b32_e32 v38, v33, v38, vcc
	v_add_u32_e32 v40, 1, v32
	global_store_dwordx2 v[60:61], v[44:45], off offset:1536
	v_ashrrev_i32_e32 v41, 31, v40
	v_pk_mul_f32 v[42:43], v[54:55], v[38:39] op_sel_hi:[1,0]
	v_pk_mul_f32 v[44:45], v[56:57], v[38:39] op_sel_hi:[1,0]
	v_pk_mul_f32 v[24:25], v[24:25], v[38:39] op_sel_hi:[1,0]
	v_pk_mul_f32 v[26:27], v[26:27], v[38:39] op_sel_hi:[1,0]
	v_pk_mul_f32 v[20:21], v[20:21], v[38:39] op_sel_hi:[1,0]
	v_pk_mul_f32 v[22:23], v[22:23], v[38:39] op_sel_hi:[1,0]
	v_pk_mul_f32 v[16:17], v[16:17], v[38:39] op_sel_hi:[1,0]
	v_pk_mul_f32 v[18:19], v[18:19], v[38:39] op_sel_hi:[1,0]
	v_lshlrev_b64 v[40:41], 11, v[40:41]
	v_pk_mul_f32 v[42:43], v[12:13], v[42:43]
	v_pk_mul_f32 v[44:45], v[14:15], v[44:45]
	v_pk_mul_f32 v[24:25], v[4:5], v[24:25]
	v_pk_mul_f32 v[26:27], v[6:7], v[26:27]
	v_pk_mul_f32 v[20:21], v[0:1], v[20:21]
	v_pk_mul_f32 v[22:23], v[2:3], v[22:23]
	v_pk_mul_f32 v[16:17], v[8:9], v[16:17]
	v_pk_mul_f32 v[18:19], v[10:11], v[18:19]
	v_lshl_add_u64 v[40:41], v[30:31], 0, v[40:41]
	v_cvt_pk_bf16_f32 v42, v42, v43
	v_cvt_pk_bf16_f32 v43, v44, v45
	v_cvt_pk_bf16_f32 v24, v24, v25
	v_cvt_pk_bf16_f32 v25, v26, v27
	v_cvt_pk_bf16_f32 v20, v20, v21
	v_cvt_pk_bf16_f32 v21, v22, v23
	v_cvt_pk_bf16_f32 v16, v16, v17
	v_cvt_pk_bf16_f32 v17, v18, v19
	v_add_u32_e32 v32, s2, v32
	global_store_dwordx2 v[40:41], v[42:43], off
	global_store_dwordx2 v[40:41], v[24:25], off offset:512
	global_store_dwordx2 v[40:41], v[20:21], off offset:1024
	global_store_dwordx2 v[40:41], v[16:17], off offset:1536
	s_cbranch_scc1 .LBB0_1875

; DI void phase_final(const Ctx& c) {
;     ...
;   for (int u = blockIdx.x; u < NTOK / 8; u += gridDim.x) {
;     float* xr = p.out + (size_t)(u * 8 + wid * 2) * 1024;
;     f32x4 v[2][4];
; #pragma unroll
;     for (int r = 0; r < 2; ++r)
; #pragma unroll
;       for (int i = 0; i < 4; ++i) v[r][i] = *(const f32x4*)(xr + r * 1024 + i * 256 + lane * 4);
; #pragma unroll
;     for (int r = 0; r < 2; ++r) {
;       float ss = 0.f;
; #pragma unroll
;       for (int i = 0; i < 4; ++i) ss += v[r][i][0] * v[r][i][0] + v[r][i][1] * v[r][i][1] + v[r][i][2] * v[r][i][2] + v[r][i][3] * v[r][i][3];
;       ss = wave_sum(ss);
;       const float rs = rsqrtf(ss * (1.0f / 1024.0f) + 1e-5f);
; #pragma unroll
;       for (int i = 0; i < 4; ++i) *(f32x4*)(xr + r * 1024 + i * 256 + lane * 4) = v[r][i] * rs * g[i];
;     }
.LBB0_1949:
	v_ashrrev_i32_e32 v19, 31, v18
	v_lshlrev_b64 v[22:23], 12, v[18:19]
	v_lshl_add_u64 v[58:59], v[16:17], 0, v[22:23]
	global_load_dwordx4 v[26:29], v[58:59], off nt
	global_load_dwordx4 v[30:33], v[58:59], off offset:1024 nt
	global_load_dwordx4 v[34:37], v[58:59], off offset:2048 nt
	global_load_dwordx4 v[38:41], v[58:59], off offset:3072 nt
	v_add_co_u32_e32 v22, vcc, 0x1000, v58
	s_add_i32 s6, s6, s1
	s_nop 0
	v_addc_co_u32_e32 v23, vcc, 0, v59, vcc
	global_load_dwordx4 v[42:45], v[22:23], off nt
	global_load_dwordx4 v[46:49], v[22:23], off offset:1024 nt
	global_load_dwordx4 v[50:53], v[22:23], off offset:2048 nt
	global_load_dwordx4 v[54:57], v[22:23], off offset:3072 nt
	s_cmpk_lt_i32 s6, 0x1000
	v_add_u32_e32 v18, s4, v18
	s_waitcnt vmcnt(7)
	v_mov_b32_e32 v62, v27
	s_waitcnt vmcnt(6)
	v_mov_b32_e32 v63, v31
	s_waitcnt vmcnt(5)
	v_mov_b32_e32 v70, v35
	s_waitcnt vmcnt(4)
	v_mov_b32_e32 v71, v39
	v_mov_b32_e32 v60, v26
	v_mov_b32_e32 v61, v30
	v_mov_b32_e32 v68, v34
	v_mov_b32_e32 v69, v38
	v_pk_mul_f32 v[62:63], v[62:63], v[62:63]
	v_pk_mul_f32 v[70:71], v[70:71], v[70:71]
	v_mov_b32_e32 v64, v28
	v_mov_b32_e32 v65, v32
	v_pk_fma_f32 v[60:61], v[60:61], v[60:61], v[62:63]
	v_pk_fma_f32 v[62:63], v[68:69], v[68:69], v[70:71]
	s_waitcnt vmcnt(3)
	v_mov_b32_e32 v70, v43
	s_waitcnt vmcnt(2)
	v_mov_b32_e32 v71, v47
	v_mov_b32_e32 v68, v42
	v_mov_b32_e32 v69, v46
	s_waitcnt vmcnt(1)
	v_mov_b32_e32 v82, v51
	s_waitcnt vmcnt(0)
	v_mov_b32_e32 v83, v55
	v_pk_fma_f32 v[60:61], v[64:65], v[64:65], v[60:61]
	v_pk_mul_f32 v[64:65], v[70:71], v[70:71]
	v_mov_b32_e32 v66, v29
	v_mov_b32_e32 v67, v33
	v_mov_b32_e32 v76, v44
	v_mov_b32_e32 v77, v48
	v_mov_b32_e32 v80, v50
	v_mov_b32_e32 v81, v54
	v_pk_mul_f32 v[70:71], v[82:83], v[82:83]
	v_pk_fma_f32 v[64:65], v[68:69], v[68:69], v[64:65]
	v_mov_b32_e32 v72, v36
	v_mov_b32_e32 v73, v40
	v_mov_b32_e32 v78, v45
	v_mov_b32_e32 v79, v49
	v_mov_b32_e32 v84, v52
	v_mov_b32_e32 v85, v56
	v_pk_fma_f32 v[60:61], v[66:67], v[66:67], v[60:61]
	v_pk_fma_f32 v[66:67], v[80:81], v[80:81], v[70:71]
	v_pk_fma_f32 v[64:65], v[76:77], v[76:77], v[64:65]
	v_mov_b32_e32 v74, v37
	v_mov_b32_e32 v75, v41
	v_mov_b32_e32 v86, v53
	v_mov_b32_e32 v87, v57
	v_pk_fma_f32 v[62:63], v[72:73], v[72:73], v[62:63]
	v_pk_fma_f32 v[66:67], v[84:85], v[84:85], v[66:67]
	v_pk_fma_f32 v[64:65], v[78:79], v[78:79], v[64:65]
	v_pk_fma_f32 v[62:63], v[74:75], v[74:75], v[62:63]
	v_mov_b32_e32 v69, v60
	v_pk_fma_f32 v[66:67], v[86:87], v[86:87], v[66:67]
	v_mov_b32_e32 v68, v64
	v_mov_b32_e32 v60, v65
	v_mov_b32_e32 v71, v62
	v_mov_b32_e32 v70, v66
	v_pk_add_f32 v[60:61], v[68:69], v[60:61]
	v_mov_b32_e32 v62, v67
	v_pk_add_f32 v[60:61], v[60:61], v[70:71]
	s_nop 0
	v_pk_add_f32 v[60:61], v[60:61], v[62:63]
	s_nop 1
	v_mov_b32_dpp v63, v61 quad_perm:[1,0,3,2] row_mask:0xf bank_mask:0xf bound_ctrl:1
	v_mov_b32_dpp v62, v60 quad_perm:[1,0,3,2] row_mask:0xf bank_mask:0xf bound_ctrl:1
	v_pk_add_f32 v[60:61], v[60:61], v[62:63]
	s_nop 1
	v_mov_b32_dpp v63, v61 quad_perm:[2,3,0,1] row_mask:0xf bank_mask:0xf bound_ctrl:1
	v_mov_b32_dpp v62, v60 quad_perm:[2,3,0,1] row_mask:0xf bank_mask:0xf bound_ctrl:1
	v_pk_add_f32 v[60:61], v[60:61], v[62:63]
	s_nop 1
	v_mov_b32_dpp v63, v61 row_half_mirror row_mask:0xf bank_mask:0xf bound_ctrl:1
	v_mov_b32_dpp v62, v60 row_half_mirror row_mask:0xf bank_mask:0xf bound_ctrl:1
	v_pk_add_f32 v[60:61], v[60:61], v[62:63]
	s_nop 1
	v_mov_b32_dpp v63, v61 row_mirror row_mask:0xf bank_mask:0xf bound_ctrl:1
	v_mov_b32_dpp v62, v60 row_mirror row_mask:0xf bank_mask:0xf bound_ctrl:1
	v_pk_add_f32 v[60:61], v[60:61], v[62:63]
	ds_bpermute_b32 v63, v24, v61
	ds_bpermute_b32 v62, v24, v60
	s_waitcnt lgkmcnt(0)
	v_pk_add_f32 v[60:61], v[60:61], v[62:63]
	ds_bpermute_b32 v63, v25, v61
	ds_bpermute_b32 v62, v25, v60
	s_waitcnt lgkmcnt(0)
	v_pk_add_f32 v[60:61], v[60:61], v[62:63]
	s_nop 0
	v_pk_fma_f32 v[60:61], v[60:61], s[0:1], v[20:21] op_sel_hi:[1,0,0]
	s_nop 0
	v_mul_f32_e32 v19, 0x4b800000, v61
	v_cmp_gt_f32_e32 vcc, s5, v61
	v_mul_f32_e32 v62, 0x4b800000, v60
	v_cmp_gt_f32_e64 s[2:3], s5, v60
	v_cndmask_b32_e32 v19, v61, v19, vcc
	v_rsq_f32_e32 v19, v19
	v_cndmask_b32_e64 v60, v60, v62, s[2:3]
	v_rsq_f32_e32 v61, v60
	v_mul_f32_e32 v60, 0x45800000, v19
	v_cndmask_b32_e32 v60, v19, v60, vcc
	v_mul_f32_e32 v62, 0x45800000, v61
	v_cndmask_b32_e64 v62, v61, v62, s[2:3]
	v_pk_mul_f32 v[26:27], v[26:27], v[60:61] op_sel_hi:[1,0]
	v_pk_mul_f32 v[28:29], v[28:29], v[60:61] op_sel_hi:[1,0]
	v_pk_mul_f32 v[30:31], v[30:31], v[60:61] op_sel_hi:[1,0]
	v_pk_mul_f32 v[32:33], v[32:33], v[60:61] op_sel_hi:[1,0]
	v_pk_mul_f32 v[34:35], v[34:35], v[60:61] op_sel_hi:[1,0]
	v_pk_mul_f32 v[36:37], v[36:37], v[60:61] op_sel_hi:[1,0]
	v_pk_mul_f32 v[38:39], v[38:39], v[60:61] op_sel_hi:[1,0]
	v_pk_mul_f32 v[40:41], v[40:41], v[60:61] op_sel_hi:[1,0]
	v_pk_mul_f32 v[42:43], v[42:43], v[62:63] op_sel_hi:[1,0]
	v_pk_mul_f32 v[44:45], v[44:45], v[62:63] op_sel_hi:[1,0]
	v_pk_mul_f32 v[28:29], v[2:3], v[28:29]
	v_pk_mul_f32 v[26:27], v[0:1], v[26:27]
	v_pk_mul_f32 v[32:33], v[6:7], v[32:33]
	v_pk_mul_f32 v[30:31], v[4:5], v[30:31]
	v_pk_mul_f32 v[36:37], v[10:11], v[36:37]
	v_pk_mul_f32 v[34:35], v[8:9], v[34:35]
	v_pk_mul_f32 v[40:41], v[14:15], v[40:41]
	v_pk_mul_f32 v[38:39], v[12:13], v[38:39]
	global_store_dwordx4 v[58:59], v[26:29], off
	global_store_dwordx4 v[58:59], v[30:33], off offset:1024
	global_store_dwordx4 v[58:59], v[34:37], off offset:2048
	global_store_dwordx4 v[58:59], v[38:41], off offset:3072
	v_pk_mul_f32 v[28:29], v[2:3], v[44:45]
	v_pk_mul_f32 v[26:27], v[0:1], v[42:43]
	global_store_dwordx4 v[22:23], v[26:29], off
	s_nop 1
	v_pk_mul_f32 v[26:27], v[46:47], v[62:63] op_sel_hi:[1,0]
	v_pk_mul_f32 v[28:29], v[48:49], v[62:63] op_sel_hi:[1,0]
	v_pk_mul_f32 v[26:27], v[4:5], v[26:27]
	v_pk_mul_f32 v[28:29], v[6:7], v[28:29]
	global_store_dwordx4 v[22:23], v[26:29], off offset:1024
	s_nop 1
	v_pk_mul_f32 v[26:27], v[50:51], v[62:63] op_sel_hi:[1,0]
	v_pk_mul_f32 v[28:29], v[52:53], v[62:63] op_sel_hi:[1,0]
	v_pk_mul_f32 v[26:27], v[8:9], v[26:27]
	v_pk_mul_f32 v[28:29], v[10:11], v[28:29]
	global_store_dwordx4 v[22:23], v[26:29], off offset:2048
	s_nop 1
	v_pk_mul_f32 v[26:27], v[54:55], v[62:63] op_sel_hi:[1,0]
	v_pk_mul_f32 v[28:29], v[56:57], v[62:63] op_sel_hi:[1,0]
	v_pk_mul_f32 v[26:27], v[12:13], v[26:27]
	v_pk_mul_f32 v[28:29], v[14:15], v[28:29]
	global_store_dwordx4 v[22:23], v[26:29], off offset:3072
	s_cbranch_scc1 .LBB0_1949
